# 128x128 GEMM k-loops of phases 1 and 4 (z tiles, kvm tiles, gate GEMM) also moved to LDS-DMA staging with a 2-deep swizzled LDS ring, all 16 fragments read up front
# speedup vs baseline: 1.0594x; 1.0385x over previous
.LBB0_123:
	s_lshl_b32 s2, s20, 10
	s_add_i32 s2, s15, s2
	v_readlane_b32 s72, v250, 53
	v_mov_b32_e32 v60, v200
	s_lshl_b64 s[8:9], s[2:3], 11
	v_readlane_b32 s80, v250, 61
	v_readlane_b32 s81, v250, 62
	v_ashrrev_i32_e32 v36, 3, v60
	v_lshlrev_b32_e32 v0, 3, v60
	s_add_u32 s8, s80, s8
	v_and_b32_e32 v181, 56, v0
	v_add_u32_e32 v42, 32, v36
	v_add_u32_e32 v48, 64, v36
	v_add_u32_e32 v54, 0x60, v36
	s_addc_u32 s9, s81, s9
	v_lshlrev_b32_e32 v196, 1, v181
	v_ashrrev_i32_e32 v37, 31, v36
	v_ashrrev_i32_e32 v43, 31, v42
	v_ashrrev_i32_e32 v49, 31, v48
	v_ashrrev_i32_e32 v55, 31, v54
	v_lshl_add_u64 v[128:129], s[6:7], 0, v[196:197]
	v_lshl_add_u64 v[130:131], s[8:9], 0, v[196:197]
	v_lshlrev_b64 v[132:133], 11, v[36:37]
	v_lshlrev_b64 v[134:135], 11, v[42:43]
	v_lshlrev_b64 v[136:137], 11, v[48:49]
	v_lshlrev_b64 v[138:139], 11, v[54:55]
	v_lshl_add_u64 v[38:39], v[128:129], 0, v[132:133]
	v_lshl_add_u64 v[40:41], v[130:131], 0, v[132:133]
	v_lshl_add_u64 v[44:45], v[128:129], 0, v[134:135]
	v_lshl_add_u64 v[46:47], v[130:131], 0, v[134:135]
	v_lshl_add_u64 v[50:51], v[128:129], 0, v[136:137]
	v_lshl_add_u64 v[52:53], v[130:131], 0, v[136:137]
	v_lshl_add_u64 v[56:57], v[128:129], 0, v[138:139]
	v_lshl_add_u64 v[58:59], v[130:131], 0, v[138:139]
	v_and_b32_e32 v242, 63, v200
	v_readfirstlane_b32 s41, v200
	v_lshrrev_b32_e32 v243, 3, v242
	v_and_b32_e32 v244, 7, v242
	v_lshrrev_b32_e32 v246, 4, v242
	s_lshr_b32 s41, s41, 6
	v_xor_b32_e32 v244, v244, v246
	v_lshlrev_b32_e32 v244, 4, v244
	v_xor_b32_e32 v246, 64, v244
	s_lshl_b32 s46, s41, 5
	v_add_u32_e32 v243, s46, v243
	v_lshlrev_b32_e32 v247, 11, v243
	v_add_u32_e32 v186, v247, v244
	v_add_u32_e32 v187, v247, v246
	v_add_u32_e32 v188, 0x8000, v186
	v_add_u32_e32 v189, 0x8000, v187
	v_add_u32_e32 v187, 0x4000, v187
	v_add_u32_e32 v189, 0x4000, v189
	v_and_b32_e32 v243, 31, v242
	v_lshrrev_b32_e32 v244, 5, v242
	v_bfe_u32 v246, v242, 1, 3
	v_xor_b32_e32 v244, v244, v246
	v_lshlrev_b32_e32 v244, 4, v244
	v_lshl_add_u32 v244, v243, 7, v244
	s_lshr_b32 s46, s41, 1
	s_lshl_b32 s46, s46, 13
	v_add_u32_e32 v190, s46, v244
	s_and_b32 s46, s41, 1
	s_lshl_b32 s46, s46, 13
	s_add_u32 s46, s46, 0x4000
	v_add_u32_e32 v194, s46, v244
	v_xor_b32_e32 v191, 32, v190
	v_xor_b32_e32 v201, 32, v194
	v_xor_b32_e32 v192, 64, v190
	v_xor_b32_e32 v206, 64, v194
	v_xor_b32_e32 v193, 96, v190
	v_xor_b32_e32 v214, 96, v194
	s_lshl_b32 s46, s41, 12
	s_add_u32 s47, s46, 0x4000
	s_mov_b32 s42, s6
	s_mov_b32 s43, s7
	s_mov_b32 s44, s8
	s_mov_b32 s45, s9
	s_mov_b32 m0, s46
	s_nop 0
	global_load_lds_dwordx4 v186, s[42:43]
	s_add_u32 m0, m0, 0x400
	s_nop 0
	global_load_lds_dwordx4 v187, s[42:43]
	s_add_u32 m0, m0, 0x400
	s_nop 0
	global_load_lds_dwordx4 v188, s[42:43]
	s_add_u32 m0, m0, 0x400
	s_nop 0
	global_load_lds_dwordx4 v189, s[42:43]
	s_mov_b32 m0, s47
	s_nop 0
	global_load_lds_dwordx4 v186, s[44:45]
	s_add_u32 m0, m0, 0x400
	s_nop 0
	global_load_lds_dwordx4 v187, s[44:45]
	s_add_u32 m0, m0, 0x400
	s_nop 0
	global_load_lds_dwordx4 v188, s[44:45]
	s_add_u32 m0, m0, 0x400
	s_nop 0
	global_load_lds_dwordx4 v189, s[44:45]
	s_add_u32 s42, s42, 128
	s_addc_u32 s43, s43, 0
	s_add_u32 s44, s44, 128
	s_addc_u32 s45, s45, 0
	v_and_b32_e32 v61, 31, v60
	v_lshrrev_b32_e32 v62, 1, v60
	v_and_b32_e32 v60, 0x5f, v60
	s_movk_i32 s2, 0x90
	s_mov_b32 s26, 0xfffffc0
	v_and_or_b32 v61, v62, s26, v61
	v_and_b32_e32 v62, 16, v62
	v_mad_u32_u24 v60, v60, s2, 0
	v_mul_lo_u32 v63, v36, s2
	v_mul_lo_u32 v61, v61, s2
	v_add_u32_e32 v182, v60, v62
	v_add_u32_e32 v60, 0, v196
	v_lshlrev_b64 v[36:37], 10, v[36:37]
	v_add_u32_e32 v96, 0x1200, v63
	v_lshlrev_b64 v[42:43], 10, v[42:43]
	v_lshlrev_b64 v[48:49], 10, v[48:49]
	v_lshlrev_b64 v[54:55], 10, v[54:55]
	v_add_u32_e32 v38, 0, v61
	v_add_u32_e32 v183, v60, v63
	s_mov_b32 s21, 0
	s_movk_i32 s22, 0x80
	v_mov_b32_e32 v0, 0
	v_mov_b32_e32 v1, v172
	v_mov_b32_e32 v2, v172
	v_mov_b32_e32 v3, v172
	v_lshlrev_b64 v[140:141], 1, v[36:37]
	v_add_u32_e32 v184, v60, v96
	v_lshlrev_b64 v[142:143], 1, v[42:43]
	v_lshlrev_b64 v[144:145], 1, v[48:49]
	v_lshlrev_b64 v[146:147], 1, v[54:55]
	v_add_u32_e32 v185, v38, v62
	v_mov_b32_e32 v36, v172
	v_mov_b32_e32 v37, v172
	v_mov_b32_e32 v38, v172
	v_mov_b32_e32 v39, v172
	v_mov_b32_e32 v40, v172
	v_mov_b32_e32 v41, v172
	v_mov_b32_e32 v42, v172
	v_mov_b32_e32 v43, v172
	v_mov_b32_e32 v44, v172
	v_mov_b32_e32 v45, v172
	v_mov_b32_e32 v46, v172
	v_mov_b32_e32 v4, v172
	v_mov_b32_e32 v5, v172
	v_mov_b32_e32 v6, v172
	v_mov_b32_e32 v7, v172
	v_mov_b32_e32 v8, v172
	v_mov_b32_e32 v9, v172
	v_mov_b32_e32 v10, v172
	v_mov_b32_e32 v11, v172
	v_mov_b32_e32 v12, v172
	v_mov_b32_e32 v13, v172
	v_mov_b32_e32 v14, v172
	v_mov_b32_e32 v15, v172
	v_mov_b32_e32 v16, 0
	v_mov_b32_e32 v17, v172
	v_mov_b32_e32 v18, v172
	v_mov_b32_e32 v19, v172
	v_mov_b32_e32 v20, v172
	v_mov_b32_e32 v21, v172
	v_mov_b32_e32 v22, v172
	v_mov_b32_e32 v23, v172
	v_mov_b32_e32 v24, v172
	v_mov_b32_e32 v25, v172
	v_mov_b32_e32 v26, v172
	v_mov_b32_e32 v27, v172
	v_mov_b32_e32 v28, v172
	v_mov_b32_e32 v29, v172
	v_mov_b32_e32 v30, v172
	v_mov_b32_e32 v31, v172
	v_mov_b32_e32 v32, 0
	v_mov_b32_e32 v33, v172
	v_mov_b32_e32 v34, v172
	v_mov_b32_e32 v35, v172
	v_mov_b32_e32 v47, v172
	v_mov_b32_e32 v48, 0
	v_mov_b32_e32 v49, v172
	v_mov_b32_e32 v50, v172
	v_mov_b32_e32 v51, v172
	v_mov_b32_e32 v52, v172
	v_mov_b32_e32 v53, v172
	v_mov_b32_e32 v54, v172
	v_mov_b32_e32 v55, v172
	v_mov_b32_e32 v56, v172
	v_mov_b32_e32 v57, v172
	v_mov_b32_e32 v58, v172
	v_mov_b32_e32 v59, v172
	v_mov_b32_e32 v60, v172
	v_mov_b32_e32 v61, v172
	v_mov_b32_e32 v62, v172
	v_mov_b32_e32 v63, v172
	v_readlane_b32 s73, v250, 54
	v_readlane_b32 s74, v250, 55
	v_readlane_b32 s75, v250, 56
	v_readlane_b32 s76, v250, 57
	v_readlane_b32 s77, v250, 58
	v_readlane_b32 s78, v250, 59
	v_readlane_b32 s79, v250, 60
	v_readlane_b32 s82, v250, 63
	v_readlane_b32 s83, v249, 0
	v_readlane_b32 s84, v249, 1
	v_readlane_b32 s85, v249, 2
	v_readlane_b32 s86, v249, 3
	v_readlane_b32 s87, v249, 4
	s_mov_b32 s49, 0x8000
	s_waitcnt vmcnt(0)
	s_waitcnt lgkmcnt(0)
	s_barrier
	s_branch .LBB0_125
.LBB0_125:
	ds_read_b128 v[64:67], v194
	ds_read_b128 v[68:71], v190
	ds_read_b128 v[72:75], v194 offset:4096
	ds_read_b128 v[76:79], v190 offset:4096
	ds_read_b128 v[80:83], v201
	ds_read_b128 v[84:87], v191
	ds_read_b128 v[88:91], v201 offset:4096
	ds_read_b128 v[92:95], v191 offset:4096
	ds_read_b128 v[96:99], v206
	ds_read_b128 v[100:103], v192
	ds_read_b128 v[104:107], v206 offset:4096
	ds_read_b128 v[108:111], v192 offset:4096
	ds_read_b128 v[112:115], v214
	ds_read_b128 v[116:119], v193
	ds_read_b128 v[120:123], v214 offset:4096
	ds_read_b128 v[124:127], v193 offset:4096
	s_add_u32 m0, s46, s49
	s_waitcnt lgkmcnt(14)
	v_mfma_f32_32x32x16_bf16 v[48:63], v[64:67], v[68:71], v[48:63]
	s_waitcnt lgkmcnt(13)
	v_mfma_f32_32x32x16_bf16 v[32:47], v[72:75], v[68:71], v[32:47]
	global_load_lds_dwordx4 v186, s[42:43]
	s_add_u32 m0, m0, 0x400
	s_waitcnt lgkmcnt(12)
	v_mfma_f32_32x32x16_bf16 v[16:31], v[64:67], v[76:79], v[16:31]
	v_mfma_f32_32x32x16_bf16 v[0:15], v[72:75], v[76:79], v[0:15]
	global_load_lds_dwordx4 v187, s[42:43]
	s_add_u32 m0, m0, 0x400
	s_waitcnt lgkmcnt(10)
	v_mfma_f32_32x32x16_bf16 v[48:63], v[80:83], v[84:87], v[48:63]
	s_waitcnt lgkmcnt(9)
	v_mfma_f32_32x32x16_bf16 v[32:47], v[88:91], v[84:87], v[32:47]
	global_load_lds_dwordx4 v188, s[42:43]
	s_add_u32 m0, m0, 0x400
	s_waitcnt lgkmcnt(8)
	v_mfma_f32_32x32x16_bf16 v[16:31], v[80:83], v[92:95], v[16:31]
	v_mfma_f32_32x32x16_bf16 v[0:15], v[88:91], v[92:95], v[0:15]
	global_load_lds_dwordx4 v189, s[42:43]
	s_add_u32 m0, s47, s49
	s_waitcnt lgkmcnt(6)
	v_mfma_f32_32x32x16_bf16 v[48:63], v[96:99], v[100:103], v[48:63]
	s_waitcnt lgkmcnt(5)
	v_mfma_f32_32x32x16_bf16 v[32:47], v[104:107], v[100:103], v[32:47]
	global_load_lds_dwordx4 v186, s[44:45]
	s_add_u32 m0, m0, 0x400
	s_waitcnt lgkmcnt(4)
	v_mfma_f32_32x32x16_bf16 v[16:31], v[96:99], v[108:111], v[16:31]
	v_mfma_f32_32x32x16_bf16 v[0:15], v[104:107], v[108:111], v[0:15]
	global_load_lds_dwordx4 v187, s[44:45]
	s_add_u32 m0, m0, 0x400
	s_waitcnt lgkmcnt(2)
	v_mfma_f32_32x32x16_bf16 v[48:63], v[112:115], v[116:119], v[48:63]
	s_waitcnt lgkmcnt(1)
	v_mfma_f32_32x32x16_bf16 v[32:47], v[120:123], v[116:119], v[32:47]
	global_load_lds_dwordx4 v188, s[44:45]
	s_add_u32 m0, m0, 0x400
	s_waitcnt lgkmcnt(0)
	v_mfma_f32_32x32x16_bf16 v[16:31], v[112:115], v[124:127], v[16:31]
	v_mfma_f32_32x32x16_bf16 v[0:15], v[120:123], v[124:127], v[0:15]
	global_load_lds_dwordx4 v189, s[44:45]
	v_xor_b32_e32 v190, 0x8000, v190
	v_xor_b32_e32 v191, 0x8000, v191
	v_xor_b32_e32 v192, 0x8000, v192
	v_xor_b32_e32 v193, 0x8000, v193
	v_xor_b32_e32 v194, 0x8000, v194
	v_xor_b32_e32 v201, 0x8000, v201
	v_xor_b32_e32 v206, 0x8000, v206
	v_xor_b32_e32 v214, 0x8000, v214
	s_xor_b32 s49, s49, 0x8000
	s_add_u32 s42, s42, 128
	s_addc_u32 s43, s43, 0
	s_add_u32 s44, s44, 128
	s_addc_u32 s45, s45, 0
	s_add_u32 s21, s21, 1
	s_waitcnt vmcnt(0)
	s_cmp_lt_u32 s21, 15
	s_barrier
	s_cbranch_scc1 .LBB0_125
.Lp4g_tail:
	ds_read_b128 v[64:67], v194
	ds_read_b128 v[68:71], v190
	ds_read_b128 v[72:75], v194 offset:4096
	ds_read_b128 v[76:79], v190 offset:4096
	ds_read_b128 v[80:83], v201
	ds_read_b128 v[84:87], v191
	ds_read_b128 v[88:91], v201 offset:4096
	ds_read_b128 v[92:95], v191 offset:4096
	ds_read_b128 v[96:99], v206
	ds_read_b128 v[100:103], v192
	ds_read_b128 v[104:107], v206 offset:4096
	ds_read_b128 v[108:111], v192 offset:4096
	ds_read_b128 v[112:115], v214
	ds_read_b128 v[116:119], v193
	ds_read_b128 v[120:123], v214 offset:4096
	ds_read_b128 v[124:127], v193 offset:4096
	s_waitcnt lgkmcnt(14)
	v_mfma_f32_32x32x16_bf16 v[48:63], v[64:67], v[68:71], v[48:63]
	s_waitcnt lgkmcnt(13)
	v_mfma_f32_32x32x16_bf16 v[32:47], v[72:75], v[68:71], v[32:47]
	s_waitcnt lgkmcnt(12)
	v_mfma_f32_32x32x16_bf16 v[16:31], v[64:67], v[76:79], v[16:31]
	v_mfma_f32_32x32x16_bf16 v[0:15], v[72:75], v[76:79], v[0:15]
	s_waitcnt lgkmcnt(10)
	v_mfma_f32_32x32x16_bf16 v[48:63], v[80:83], v[84:87], v[48:63]
	s_waitcnt lgkmcnt(9)
	v_mfma_f32_32x32x16_bf16 v[32:47], v[88:91], v[84:87], v[32:47]
	s_waitcnt lgkmcnt(8)
	v_mfma_f32_32x32x16_bf16 v[16:31], v[80:83], v[92:95], v[16:31]
	v_mfma_f32_32x32x16_bf16 v[0:15], v[88:91], v[92:95], v[0:15]
	s_waitcnt lgkmcnt(6)
	v_mfma_f32_32x32x16_bf16 v[48:63], v[96:99], v[100:103], v[48:63]
	s_waitcnt lgkmcnt(5)
	v_mfma_f32_32x32x16_bf16 v[32:47], v[104:107], v[100:103], v[32:47]
	s_waitcnt lgkmcnt(4)
	v_mfma_f32_32x32x16_bf16 v[16:31], v[96:99], v[108:111], v[16:31]
	v_mfma_f32_32x32x16_bf16 v[0:15], v[104:107], v[108:111], v[0:15]
	s_waitcnt lgkmcnt(2)
	v_mfma_f32_32x32x16_bf16 v[48:63], v[112:115], v[116:119], v[48:63]
	s_waitcnt lgkmcnt(1)
	v_mfma_f32_32x32x16_bf16 v[32:47], v[120:123], v[116:119], v[32:47]
	s_waitcnt lgkmcnt(0)
	v_mfma_f32_32x32x16_bf16 v[16:31], v[112:115], v[124:127], v[16:31]
	v_mfma_f32_32x32x16_bf16 v[0:15], v[120:123], v[124:127], v[0:15]
	v_xor_b32_e32 v190, 0x8000, v190
	v_xor_b32_e32 v191, 0x8000, v191
	v_xor_b32_e32 v192, 0x8000, v192
	v_xor_b32_e32 v193, 0x8000, v193
	v_xor_b32_e32 v194, 0x8000, v194
	v_xor_b32_e32 v201, 0x8000, v201
	v_xor_b32_e32 v206, 0x8000, v206
	v_xor_b32_e32 v214, 0x8000, v214
	s_add_u32 s21, s21, 1
	s_waitcnt vmcnt(0)
	s_cmp_lt_u32 s21, 16
	s_barrier
	s_branch .LBB0_127

.LBB0_416:
	s_and_b32 s0, s0, 15
	s_or_b32 s18, s0, s50
	v_readlane_b32 s72, v250, 53
	s_lshl_b32 s0, s18, 18
	v_readlane_b32 s78, v250, 59
	v_readlane_b32 s79, v250, 60
	s_add_u32 s4, s78, s0
	v_mov_b32_e32 v3, v200
	v_readlane_b32 s80, v250, 61
	s_addc_u32 s5, s79, 0
	s_lshl_b32 s0, s17, 18
	v_ashrrev_i32_e32 v36, 3, v3
	v_lshlrev_b32_e32 v0, 3, v3
	v_readlane_b32 s81, v250, 62
	s_waitcnt vmcnt(0)
	v_and_b32_e32 v148, 56, v0
	s_add_u32 s6, s80, s0
	v_add_u32_e32 v40, 32, v36
	v_add_u32_e32 v44, 64, v36
	v_add_u32_e32 v48, 0x60, v36
	v_lshlrev_b32_e32 v196, 1, v148
	v_ashrrev_i32_e32 v37, 31, v36
	v_ashrrev_i32_e32 v41, 31, v40
	s_addc_u32 s7, s81, 0
	v_ashrrev_i32_e32 v45, 31, v44
	v_ashrrev_i32_e32 v49, 31, v48
	v_lshl_add_u64 v[128:129], s[4:5], 0, v[196:197]
	v_lshlrev_b64 v[130:131], 11, v[36:37]
	v_lshlrev_b64 v[132:133], 11, v[40:41]
	v_lshlrev_b64 v[134:135], 11, v[44:45]
	v_lshlrev_b64 v[136:137], 11, v[48:49]
	v_lshl_add_u64 v[138:139], s[6:7], 0, v[196:197]
	v_lshl_add_u64 v[38:39], v[128:129], 0, v[130:131]
	v_lshl_add_u64 v[42:43], v[128:129], 0, v[132:133]
	v_lshl_add_u64 v[46:47], v[128:129], 0, v[134:135]
	v_lshl_add_u64 v[50:51], v[128:129], 0, v[136:137]
	v_lshl_add_u64 v[52:53], v[138:139], 0, v[130:131]
	v_lshl_add_u64 v[54:55], v[138:139], 0, v[132:133]
	v_and_b32_e32 v184, 63, v200
	v_readfirstlane_b32 s2, v200
	v_lshrrev_b32_e32 v185, 3, v184
	v_and_b32_e32 v186, 7, v184
	v_lshrrev_b32_e32 v187, 4, v184
	s_lshr_b32 s2, s2, 6
	v_xor_b32_e32 v186, v186, v187
	v_lshlrev_b32_e32 v186, 4, v186
	v_xor_b32_e32 v187, 64, v186
	s_lshl_b32 s32, s2, 5
	v_add_u32_e32 v185, s32, v185
	v_lshlrev_b32_e32 v188, 11, v185
	v_add_u32_e32 v166, v188, v186
	v_add_u32_e32 v167, v188, v187
	v_add_u32_e32 v168, 0x8000, v166
	v_add_u32_e32 v169, 0x8000, v167
	v_add_u32_e32 v167, 0x4000, v167
	v_add_u32_e32 v169, 0x4000, v169
	v_and_b32_e32 v185, 31, v184
	v_lshrrev_b32_e32 v186, 5, v184
	v_bfe_u32 v187, v184, 1, 3
	v_xor_b32_e32 v186, v186, v187
	v_lshlrev_b32_e32 v186, 4, v186
	v_lshl_add_u32 v186, v185, 7, v186
	s_lshr_b32 s32, s2, 1
	s_lshl_b32 s32, s32, 13
	v_add_u32_e32 v170, s32, v186
	s_and_b32 s32, s2, 1
	s_lshl_b32 s32, s32, 13
	s_add_u32 s32, s32, 0x4000
	v_add_u32_e32 v174, s32, v186
	v_xor_b32_e32 v171, 32, v170
	v_xor_b32_e32 v175, 32, v174
	v_xor_b32_e32 v172, 64, v170
	v_xor_b32_e32 v176, 64, v174
	v_xor_b32_e32 v173, 96, v170
	v_xor_b32_e32 v177, 96, v174
	s_lshl_b32 s32, s2, 12
	s_add_u32 s49, s32, 0x4000
	s_mov_b32 s8, s4
	s_mov_b32 s9, s5
	s_mov_b32 s46, s6
	s_mov_b32 s47, s7
	s_mov_b32 m0, s32
	s_nop 0
	global_load_lds_dwordx4 v166, s[8:9]
	s_add_u32 m0, m0, 0x400
	s_nop 0
	global_load_lds_dwordx4 v167, s[8:9]
	s_add_u32 m0, m0, 0x400
	s_nop 0
	global_load_lds_dwordx4 v168, s[8:9]
	s_add_u32 m0, m0, 0x400
	s_nop 0
	global_load_lds_dwordx4 v169, s[8:9]
	s_mov_b32 m0, s49
	s_nop 0
	global_load_lds_dwordx4 v166, s[46:47]
	s_add_u32 m0, m0, 0x400
	s_nop 0
	global_load_lds_dwordx4 v167, s[46:47]
	s_add_u32 m0, m0, 0x400
	s_nop 0
	global_load_lds_dwordx4 v168, s[46:47]
	s_add_u32 m0, m0, 0x400
	s_nop 0
	global_load_lds_dwordx4 v169, s[46:47]
	s_add_u32 s8, s8, 128
	s_addc_u32 s9, s9, 0
	s_add_u32 s46, s46, 128
	s_addc_u32 s47, s47, 0
	v_lshl_add_u64 v[56:57], v[138:139], 0, v[134:135]
	v_lshl_add_u64 v[58:59], v[138:139], 0, v[136:137]
	v_and_b32_e32 v60, 31, v3
	v_lshrrev_b32_e32 v61, 1, v3
	v_and_b32_e32 v3, 0x5f, v3
	s_movk_i32 s2, 0x90
	v_and_or_b32 v60, v61, s23, v60
	v_and_b32_e32 v61, 16, v61
	v_mad_u32_u24 v3, v3, s2, 0
	v_mul_lo_u32 v62, v36, s2
	v_mul_lo_u32 v60, v60, s2
	v_add_u32_e32 v149, v3, v61
	v_add_u32_e32 v3, 0, v196
	v_mov_b32_e32 v0, 0
	v_add_u32_e32 v63, 0x1200, v62
	v_lshlrev_b64 v[36:37], 10, v[36:37]
	v_lshlrev_b64 v[40:41], 10, v[40:41]
	v_lshlrev_b64 v[44:45], 10, v[44:45]
	v_lshlrev_b64 v[48:49], 10, v[48:49]
	v_add_u32_e32 v60, 0, v60
	v_add_u32_e32 v150, v3, v62
	s_movk_i32 s0, 0x80
	s_mov_b32 s1, 0
	v_mov_b32_e32 v1, v0
	v_mov_b32_e32 v2, v0
	v_lshlrev_b64 v[140:141], 1, v[36:37]
	v_add_u32_e32 v151, v3, v63
	v_lshlrev_b64 v[142:143], 1, v[40:41]
	v_lshlrev_b64 v[144:145], 1, v[44:45]
	v_lshlrev_b64 v[146:147], 1, v[48:49]
	v_add_u32_e32 v152, v60, v61
	v_mov_b32_e32 v3, v0
	v_mov_b32_e32 v36, v0
	v_mov_b32_e32 v37, v0
	v_mov_b32_e32 v38, v0
	v_mov_b32_e32 v39, v0
	v_mov_b32_e32 v40, v0
	v_mov_b32_e32 v41, v0
	v_mov_b32_e32 v42, v0
	v_mov_b32_e32 v43, v0
	v_mov_b32_e32 v44, v0
	v_mov_b32_e32 v45, v0
	v_mov_b32_e32 v46, v0
	v_mov_b32_e32 v47, v0
	v_mov_b32_e32 v4, v0
	v_mov_b32_e32 v5, v0
	v_mov_b32_e32 v6, v0
	v_mov_b32_e32 v7, v0
	v_mov_b32_e32 v8, v0
	v_mov_b32_e32 v9, v0
	v_mov_b32_e32 v10, v0
	v_mov_b32_e32 v11, v0
	v_mov_b32_e32 v12, v0
	v_mov_b32_e32 v13, v0
	v_mov_b32_e32 v14, v0
	v_mov_b32_e32 v15, v0
	v_mov_b32_e32 v16, v0
	v_mov_b32_e32 v17, v0
	v_mov_b32_e32 v18, v0
	v_mov_b32_e32 v19, v0
	v_mov_b32_e32 v20, v0
	v_mov_b32_e32 v21, v0
	v_mov_b32_e32 v22, v0
	v_mov_b32_e32 v23, v0
	v_mov_b32_e32 v24, v0
	v_mov_b32_e32 v25, v0
	v_mov_b32_e32 v26, v0
	v_mov_b32_e32 v27, v0
	v_mov_b32_e32 v28, v0
	v_mov_b32_e32 v29, v0
	v_mov_b32_e32 v30, v0
	v_mov_b32_e32 v31, v0
	v_mov_b32_e32 v32, v0
	v_mov_b32_e32 v33, v0
	v_mov_b32_e32 v34, v0
	v_mov_b32_e32 v35, v0
	v_mov_b32_e32 v48, v0
	v_mov_b32_e32 v49, v0
	v_mov_b32_e32 v50, v0
	v_mov_b32_e32 v51, v0
	v_mov_b32_e32 v52, v0
	v_mov_b32_e32 v53, v0
	v_mov_b32_e32 v54, v0
	v_mov_b32_e32 v55, v0
	v_mov_b32_e32 v56, v0
	v_mov_b32_e32 v57, v0
	v_mov_b32_e32 v58, v0
	v_mov_b32_e32 v59, v0
	v_mov_b32_e32 v60, v0
	v_mov_b32_e32 v61, v0
	v_mov_b32_e32 v62, v0
	v_mov_b32_e32 v63, v0
	v_readlane_b32 s73, v250, 54
	v_readlane_b32 s74, v250, 55
	v_readlane_b32 s75, v250, 56
	v_readlane_b32 s76, v250, 57
	v_readlane_b32 s77, v250, 58
	v_readlane_b32 s82, v250, 63
	v_readlane_b32 s83, v249, 0
	v_readlane_b32 s84, v249, 1
	v_readlane_b32 s85, v249, 2
	v_readlane_b32 s86, v249, 3
	v_readlane_b32 s87, v249, 4
	s_mov_b32 s0, 0x8000
	s_waitcnt vmcnt(0)
	s_waitcnt lgkmcnt(0)
	s_barrier
	s_branch .LBB0_418
.LBB0_418:
	ds_read_b128 v[64:67], v174
	ds_read_b128 v[68:71], v170
	ds_read_b128 v[72:75], v174 offset:4096
	ds_read_b128 v[76:79], v170 offset:4096
	ds_read_b128 v[80:83], v175
	ds_read_b128 v[84:87], v171
	ds_read_b128 v[88:91], v175 offset:4096
	ds_read_b128 v[92:95], v171 offset:4096
	ds_read_b128 v[96:99], v176
	ds_read_b128 v[100:103], v172
	ds_read_b128 v[104:107], v176 offset:4096
	ds_read_b128 v[108:111], v172 offset:4096
	ds_read_b128 v[112:115], v177
	ds_read_b128 v[116:119], v173
	ds_read_b128 v[120:123], v177 offset:4096
	ds_read_b128 v[124:127], v173 offset:4096
	s_add_u32 m0, s32, s0
	s_waitcnt lgkmcnt(14)
	v_mfma_f32_32x32x16_bf16 v[48:63], v[64:67], v[68:71], v[48:63]
	s_waitcnt lgkmcnt(13)
	v_mfma_f32_32x32x16_bf16 v[32:47], v[72:75], v[68:71], v[32:47]
	global_load_lds_dwordx4 v166, s[8:9]
	s_add_u32 m0, m0, 0x400
	s_waitcnt lgkmcnt(12)
	v_mfma_f32_32x32x16_bf16 v[16:31], v[64:67], v[76:79], v[16:31]
	v_mfma_f32_32x32x16_bf16 v[0:15], v[72:75], v[76:79], v[0:15]
	global_load_lds_dwordx4 v167, s[8:9]
	s_add_u32 m0, m0, 0x400
	s_waitcnt lgkmcnt(10)
	v_mfma_f32_32x32x16_bf16 v[48:63], v[80:83], v[84:87], v[48:63]
	s_waitcnt lgkmcnt(9)
	v_mfma_f32_32x32x16_bf16 v[32:47], v[88:91], v[84:87], v[32:47]
	global_load_lds_dwordx4 v168, s[8:9]
	s_add_u32 m0, m0, 0x400
	s_waitcnt lgkmcnt(8)
	v_mfma_f32_32x32x16_bf16 v[16:31], v[80:83], v[92:95], v[16:31]
	v_mfma_f32_32x32x16_bf16 v[0:15], v[88:91], v[92:95], v[0:15]
	global_load_lds_dwordx4 v169, s[8:9]
	s_add_u32 m0, s49, s0
	s_waitcnt lgkmcnt(6)
	v_mfma_f32_32x32x16_bf16 v[48:63], v[96:99], v[100:103], v[48:63]
	s_waitcnt lgkmcnt(5)
	v_mfma_f32_32x32x16_bf16 v[32:47], v[104:107], v[100:103], v[32:47]
	global_load_lds_dwordx4 v166, s[46:47]
	s_add_u32 m0, m0, 0x400
	s_waitcnt lgkmcnt(4)
	v_mfma_f32_32x32x16_bf16 v[16:31], v[96:99], v[108:111], v[16:31]
	v_mfma_f32_32x32x16_bf16 v[0:15], v[104:107], v[108:111], v[0:15]
	global_load_lds_dwordx4 v167, s[46:47]
	s_add_u32 m0, m0, 0x400
	s_waitcnt lgkmcnt(2)
	v_mfma_f32_32x32x16_bf16 v[48:63], v[112:115], v[116:119], v[48:63]
	s_waitcnt lgkmcnt(1)
	v_mfma_f32_32x32x16_bf16 v[32:47], v[120:123], v[116:119], v[32:47]
	global_load_lds_dwordx4 v168, s[46:47]
	s_add_u32 m0, m0, 0x400
	s_waitcnt lgkmcnt(0)
	v_mfma_f32_32x32x16_bf16 v[16:31], v[112:115], v[124:127], v[16:31]
	v_mfma_f32_32x32x16_bf16 v[0:15], v[120:123], v[124:127], v[0:15]
	global_load_lds_dwordx4 v169, s[46:47]
	v_xor_b32_e32 v170, 0x8000, v170
	v_xor_b32_e32 v171, 0x8000, v171
	v_xor_b32_e32 v172, 0x8000, v172
	v_xor_b32_e32 v173, 0x8000, v173
	v_xor_b32_e32 v174, 0x8000, v174
	v_xor_b32_e32 v175, 0x8000, v175
	v_xor_b32_e32 v176, 0x8000, v176
	v_xor_b32_e32 v177, 0x8000, v177
	s_xor_b32 s0, s0, 0x8000
	s_add_u32 s8, s8, 128
	s_addc_u32 s9, s9, 0
	s_add_u32 s46, s46, 128
	s_addc_u32 s47, s47, 0
	s_add_u32 s1, s1, 1
	s_waitcnt vmcnt(0)
	s_cmp_lt_u32 s1, 15
	s_barrier
	s_cbranch_scc1 .LBB0_418
.Lp1z_tail:
	ds_read_b128 v[64:67], v174
	ds_read_b128 v[68:71], v170
	ds_read_b128 v[72:75], v174 offset:4096
	ds_read_b128 v[76:79], v170 offset:4096
	ds_read_b128 v[80:83], v175
	ds_read_b128 v[84:87], v171
	ds_read_b128 v[88:91], v175 offset:4096
	ds_read_b128 v[92:95], v171 offset:4096
	ds_read_b128 v[96:99], v176
	ds_read_b128 v[100:103], v172
	ds_read_b128 v[104:107], v176 offset:4096
	ds_read_b128 v[108:111], v172 offset:4096
	ds_read_b128 v[112:115], v177
	ds_read_b128 v[116:119], v173
	ds_read_b128 v[120:123], v177 offset:4096
	ds_read_b128 v[124:127], v173 offset:4096
	s_waitcnt lgkmcnt(14)
	v_mfma_f32_32x32x16_bf16 v[48:63], v[64:67], v[68:71], v[48:63]
	s_waitcnt lgkmcnt(13)
	v_mfma_f32_32x32x16_bf16 v[32:47], v[72:75], v[68:71], v[32:47]
	s_waitcnt lgkmcnt(12)
	v_mfma_f32_32x32x16_bf16 v[16:31], v[64:67], v[76:79], v[16:31]
	v_mfma_f32_32x32x16_bf16 v[0:15], v[72:75], v[76:79], v[0:15]
	s_waitcnt lgkmcnt(10)
	v_mfma_f32_32x32x16_bf16 v[48:63], v[80:83], v[84:87], v[48:63]
	s_waitcnt lgkmcnt(9)
	v_mfma_f32_32x32x16_bf16 v[32:47], v[88:91], v[84:87], v[32:47]
	s_waitcnt lgkmcnt(8)
	v_mfma_f32_32x32x16_bf16 v[16:31], v[80:83], v[92:95], v[16:31]
	v_mfma_f32_32x32x16_bf16 v[0:15], v[88:91], v[92:95], v[0:15]
	s_waitcnt lgkmcnt(6)
	v_mfma_f32_32x32x16_bf16 v[48:63], v[96:99], v[100:103], v[48:63]
	s_waitcnt lgkmcnt(5)
	v_mfma_f32_32x32x16_bf16 v[32:47], v[104:107], v[100:103], v[32:47]
	s_waitcnt lgkmcnt(4)
	v_mfma_f32_32x32x16_bf16 v[16:31], v[96:99], v[108:111], v[16:31]
	v_mfma_f32_32x32x16_bf16 v[0:15], v[104:107], v[108:111], v[0:15]
	s_waitcnt lgkmcnt(2)
	v_mfma_f32_32x32x16_bf16 v[48:63], v[112:115], v[116:119], v[48:63]
	s_waitcnt lgkmcnt(1)
	v_mfma_f32_32x32x16_bf16 v[32:47], v[120:123], v[116:119], v[32:47]
	s_waitcnt lgkmcnt(0)
	v_mfma_f32_32x32x16_bf16 v[16:31], v[112:115], v[124:127], v[16:31]
	v_mfma_f32_32x32x16_bf16 v[0:15], v[120:123], v[124:127], v[0:15]
	v_xor_b32_e32 v170, 0x8000, v170
	v_xor_b32_e32 v171, 0x8000, v171
	v_xor_b32_e32 v172, 0x8000, v172
	v_xor_b32_e32 v173, 0x8000, v173
	v_xor_b32_e32 v174, 0x8000, v174
	v_xor_b32_e32 v175, 0x8000, v175
	v_xor_b32_e32 v176, 0x8000, v176
	v_xor_b32_e32 v177, 0x8000, v177
	s_add_u32 s1, s1, 1
	s_waitcnt vmcnt(0)
	s_cmp_lt_u32 s1, 16
	s_barrier
	s_branch .LBB0_420

.LBB0_448:
	s_ashr_i32 s6, s12, 3
	s_ashr_i32 s7, s6, 31
	s_and_b32 s1, s12, 7
	s_lshl_b64 s[4:5], s[6:7], 17
	s_lshl_b64 s[6:7], s[6:7], 18
	s_add_u32 s6, s56, s6
	v_readlane_b32 s16, v250, 53
	v_mov_b32_e32 v1, v200
	s_addc_u32 s7, s57, s7
	s_lshl_b32 s2, s1, 18
	v_readlane_b32 s30, v249, 3
	v_readlane_b32 s31, v249, 4
	v_ashrrev_i32_e32 v34, 3, v1
	v_lshlrev_b32_e32 v0, 3, v1
	s_add_u32 s8, s30, s2
	s_waitcnt vmcnt(0)
	v_and_b32_e32 v148, 56, v0
	v_add_u32_e32 v40, 32, v34
	v_add_u32_e32 v46, 64, v34
	v_add_u32_e32 v50, 0x60, v34
	s_addc_u32 s9, s31, 0
	v_lshlrev_b32_e32 v196, 1, v148
	v_ashrrev_i32_e32 v35, 31, v34
	v_ashrrev_i32_e32 v41, 31, v40
	v_ashrrev_i32_e32 v47, 31, v46
	v_ashrrev_i32_e32 v51, 31, v50
	v_lshl_add_u64 v[128:129], s[6:7], 0, v[196:197]
	v_lshl_add_u64 v[130:131], s[8:9], 0, v[196:197]
	v_lshlrev_b64 v[132:133], 11, v[34:35]
	v_lshlrev_b64 v[134:135], 11, v[40:41]
	v_lshlrev_b64 v[136:137], 11, v[46:47]
	v_lshlrev_b64 v[138:139], 11, v[50:51]
	v_lshl_add_u64 v[36:37], v[128:129], 0, v[132:133]
	v_lshl_add_u64 v[38:39], v[130:131], 0, v[132:133]
	v_lshl_add_u64 v[42:43], v[128:129], 0, v[134:135]
	v_lshl_add_u64 v[44:45], v[130:131], 0, v[134:135]
	v_lshl_add_u64 v[48:49], v[128:129], 0, v[136:137]
	v_lshl_add_u64 v[52:53], v[128:129], 0, v[138:139]
	v_lshl_add_u64 v[54:55], v[130:131], 0, v[136:137]
	v_lshl_add_u64 v[56:57], v[130:131], 0, v[138:139]
	v_and_b32_e32 v184, 63, v200
	v_readfirstlane_b32 s2, v200
	v_lshrrev_b32_e32 v185, 3, v184
	v_and_b32_e32 v186, 7, v184
	v_lshrrev_b32_e32 v187, 4, v184
	s_lshr_b32 s2, s2, 6
	v_xor_b32_e32 v186, v186, v187
	v_lshlrev_b32_e32 v186, 4, v186
	v_xor_b32_e32 v187, 64, v186
	s_lshl_b32 s32, s2, 5
	v_add_u32_e32 v185, s32, v185
	v_lshlrev_b32_e32 v188, 11, v185
	v_add_u32_e32 v166, v188, v186
	v_add_u32_e32 v167, v188, v187
	v_add_u32_e32 v168, 0x8000, v166
	v_add_u32_e32 v169, 0x8000, v167
	v_add_u32_e32 v167, 0x4000, v167
	v_add_u32_e32 v169, 0x4000, v169
	v_and_b32_e32 v185, 31, v184
	v_lshrrev_b32_e32 v186, 5, v184
	v_bfe_u32 v187, v184, 1, 3
	v_xor_b32_e32 v186, v186, v187
	v_lshlrev_b32_e32 v186, 4, v186
	v_lshl_add_u32 v186, v185, 7, v186
	s_lshr_b32 s32, s2, 1
	s_lshl_b32 s32, s32, 13
	v_add_u32_e32 v170, s32, v186
	s_and_b32 s32, s2, 1
	s_lshl_b32 s32, s32, 13
	s_add_u32 s32, s32, 0x4000
	v_add_u32_e32 v174, s32, v186
	v_xor_b32_e32 v171, 32, v170
	v_xor_b32_e32 v175, 32, v174
	v_xor_b32_e32 v172, 64, v170
	v_xor_b32_e32 v176, 64, v174
	v_xor_b32_e32 v173, 96, v170
	v_xor_b32_e32 v177, 96, v174
	s_lshl_b32 s32, s2, 12
	s_add_u32 s49, s32, 0x4000
	s_mov_b32 s10, s6
	s_mov_b32 s11, s7
	s_mov_b32 s46, s8
	s_mov_b32 s47, s9
	s_mov_b32 m0, s32
	s_nop 0
	global_load_lds_dwordx4 v166, s[10:11]
	s_add_u32 m0, m0, 0x400
	s_nop 0
	global_load_lds_dwordx4 v167, s[10:11]
	s_add_u32 m0, m0, 0x400
	s_nop 0
	global_load_lds_dwordx4 v168, s[10:11]
	s_add_u32 m0, m0, 0x400
	s_nop 0
	global_load_lds_dwordx4 v169, s[10:11]
	s_mov_b32 m0, s49
	s_nop 0
	global_load_lds_dwordx4 v166, s[46:47]
	s_add_u32 m0, m0, 0x400
	s_nop 0
	global_load_lds_dwordx4 v167, s[46:47]
	s_add_u32 m0, m0, 0x400
	s_nop 0
	global_load_lds_dwordx4 v168, s[46:47]
	s_add_u32 m0, m0, 0x400
	s_nop 0
	global_load_lds_dwordx4 v169, s[46:47]
	s_add_u32 s10, s10, 128
	s_addc_u32 s11, s11, 0
	s_add_u32 s46, s46, 128
	s_addc_u32 s47, s47, 0
	v_and_b32_e32 v58, 31, v1
	v_lshrrev_b32_e32 v59, 1, v1
	v_and_b32_e32 v1, 0x5f, v1
	s_movk_i32 s2, 0x90
	v_and_or_b32 v58, v59, s10, v58
	v_and_b32_e32 v59, 16, v59
	v_mad_u32_u24 v1, v1, s2, 0
	v_mul_lo_u32 v60, v34, s2
	v_mul_lo_u32 v58, v58, s2
	v_add_u32_e32 v149, v1, v59
	v_add_u32_e32 v1, 0, v196
	v_mov_b32_e32 v0, 0
	v_lshlrev_b64 v[34:35], 10, v[34:35]
	v_add_u32_e32 v61, 0x1200, v60
	v_lshlrev_b64 v[40:41], 10, v[40:41]
	v_lshlrev_b64 v[46:47], 10, v[46:47]
	v_lshlrev_b64 v[50:51], 10, v[50:51]
	v_add_u32_e32 v58, 0, v58
	v_add_u32_e32 v150, v1, v60
	s_mov_b32 s13, 0
	s_movk_i32 s14, 0x80
	v_lshlrev_b64 v[140:141], 1, v[34:35]
	v_add_u32_e32 v151, v1, v61
	v_lshlrev_b64 v[142:143], 1, v[40:41]
	v_lshlrev_b64 v[144:145], 1, v[46:47]
	v_lshlrev_b64 v[146:147], 1, v[50:51]
	v_add_u32_e32 v152, v58, v59
	v_mov_b32_e32 v1, v0
	v_mov_b32_e32 v34, v0
	v_mov_b32_e32 v35, v0
	v_mov_b32_e32 v36, v0
	v_mov_b32_e32 v37, v0
	v_mov_b32_e32 v38, v0
	v_mov_b32_e32 v39, v0
	v_mov_b32_e32 v40, v0
	v_mov_b32_e32 v41, v0
	v_mov_b32_e32 v42, v0
	v_mov_b32_e32 v43, v0
	v_mov_b32_e32 v2, v0
	v_mov_b32_e32 v3, v0
	v_mov_b32_e32 v4, v0
	v_mov_b32_e32 v5, v0
	v_mov_b32_e32 v6, v0
	v_mov_b32_e32 v7, v0
	v_mov_b32_e32 v8, v0
	v_mov_b32_e32 v9, v0
	v_mov_b32_e32 v10, v0
	v_mov_b32_e32 v11, v0
	v_mov_b32_e32 v12, v0
	v_mov_b32_e32 v13, v0
	v_mov_b32_e32 v14, v0
	v_mov_b32_e32 v15, v0
	v_mov_b32_e32 v16, v0
	v_mov_b32_e32 v17, v0
	v_mov_b32_e32 v18, v0
	v_mov_b32_e32 v19, v0
	v_mov_b32_e32 v20, v0
	v_mov_b32_e32 v21, v0
	v_mov_b32_e32 v22, v0
	v_mov_b32_e32 v23, v0
	v_mov_b32_e32 v24, v0
	v_mov_b32_e32 v25, v0
	v_mov_b32_e32 v26, v0
	v_mov_b32_e32 v27, v0
	v_mov_b32_e32 v28, v0
	v_mov_b32_e32 v29, v0
	v_mov_b32_e32 v30, v0
	v_mov_b32_e32 v31, v0
	v_mov_b32_e32 v32, v0
	v_mov_b32_e32 v33, v0
	v_mov_b32_e32 v44, v0
	v_mov_b32_e32 v45, v0
	v_mov_b32_e32 v46, v0
	v_mov_b32_e32 v47, v0
	v_mov_b32_e32 v48, v0
	v_mov_b32_e32 v49, v0
	v_mov_b32_e32 v50, v0
	v_mov_b32_e32 v51, v0
	v_mov_b32_e32 v52, v0
	v_mov_b32_e32 v53, v0
	v_mov_b32_e32 v54, v0
	v_mov_b32_e32 v55, v0
	v_mov_b32_e32 v56, v0
	v_mov_b32_e32 v57, v0
	v_mov_b32_e32 v58, v0
	v_mov_b32_e32 v59, v0
	v_mov_b32_e32 v60, v0
	v_mov_b32_e32 v61, v0
	v_mov_b32_e32 v62, v0
	v_mov_b32_e32 v63, v0
	s_mov_b32 s15, 0xfffffc0
	v_readlane_b32 s17, v250, 54
	v_readlane_b32 s18, v250, 55
	v_readlane_b32 s19, v250, 56
	v_readlane_b32 s20, v250, 57
	v_readlane_b32 s21, v250, 58
	v_readlane_b32 s22, v250, 59
	v_readlane_b32 s23, v250, 60
	v_readlane_b32 s24, v250, 61
	v_readlane_b32 s25, v250, 62
	v_readlane_b32 s26, v250, 63
	v_readlane_b32 s27, v249, 0
	v_readlane_b32 s28, v249, 1
	v_readlane_b32 s29, v249, 2
	s_mov_b32 s14, 0x8000
	s_waitcnt vmcnt(0)
	s_waitcnt lgkmcnt(0)
	s_barrier
	s_branch .LBB0_450
.LBB0_450:
	ds_read_b128 v[64:67], v174
	ds_read_b128 v[68:71], v170
	ds_read_b128 v[72:75], v174 offset:4096
	ds_read_b128 v[76:79], v170 offset:4096
	ds_read_b128 v[80:83], v175
	ds_read_b128 v[84:87], v171
	ds_read_b128 v[88:91], v175 offset:4096
	ds_read_b128 v[92:95], v171 offset:4096
	ds_read_b128 v[96:99], v176
	ds_read_b128 v[100:103], v172
	ds_read_b128 v[104:107], v176 offset:4096
	ds_read_b128 v[108:111], v172 offset:4096
	ds_read_b128 v[112:115], v177
	ds_read_b128 v[116:119], v173
	ds_read_b128 v[120:123], v177 offset:4096
	ds_read_b128 v[124:127], v173 offset:4096
	s_add_u32 m0, s32, s14
	s_waitcnt lgkmcnt(14)
	v_mfma_f32_32x32x16_bf16 v[48:63], v[64:67], v[68:71], v[48:63]
	s_waitcnt lgkmcnt(13)
	v_mfma_f32_32x32x16_bf16 v[32:47], v[72:75], v[68:71], v[32:47]
	global_load_lds_dwordx4 v166, s[10:11]
	s_add_u32 m0, m0, 0x400
	s_waitcnt lgkmcnt(12)
	v_mfma_f32_32x32x16_bf16 v[16:31], v[64:67], v[76:79], v[16:31]
	v_mfma_f32_32x32x16_bf16 v[0:15], v[72:75], v[76:79], v[0:15]
	global_load_lds_dwordx4 v167, s[10:11]
	s_add_u32 m0, m0, 0x400
	s_waitcnt lgkmcnt(10)
	v_mfma_f32_32x32x16_bf16 v[48:63], v[80:83], v[84:87], v[48:63]
	s_waitcnt lgkmcnt(9)
	v_mfma_f32_32x32x16_bf16 v[32:47], v[88:91], v[84:87], v[32:47]
	global_load_lds_dwordx4 v168, s[10:11]
	s_add_u32 m0, m0, 0x400
	s_waitcnt lgkmcnt(8)
	v_mfma_f32_32x32x16_bf16 v[16:31], v[80:83], v[92:95], v[16:31]
	v_mfma_f32_32x32x16_bf16 v[0:15], v[88:91], v[92:95], v[0:15]
	global_load_lds_dwordx4 v169, s[10:11]
	s_add_u32 m0, s49, s14
	s_waitcnt lgkmcnt(6)
	v_mfma_f32_32x32x16_bf16 v[48:63], v[96:99], v[100:103], v[48:63]
	s_waitcnt lgkmcnt(5)
	v_mfma_f32_32x32x16_bf16 v[32:47], v[104:107], v[100:103], v[32:47]
	global_load_lds_dwordx4 v166, s[46:47]
	s_add_u32 m0, m0, 0x400
	s_waitcnt lgkmcnt(4)
	v_mfma_f32_32x32x16_bf16 v[16:31], v[96:99], v[108:111], v[16:31]
	v_mfma_f32_32x32x16_bf16 v[0:15], v[104:107], v[108:111], v[0:15]
	global_load_lds_dwordx4 v167, s[46:47]
	s_add_u32 m0, m0, 0x400
	s_waitcnt lgkmcnt(2)
	v_mfma_f32_32x32x16_bf16 v[48:63], v[112:115], v[116:119], v[48:63]
	s_waitcnt lgkmcnt(1)
	v_mfma_f32_32x32x16_bf16 v[32:47], v[120:123], v[116:119], v[32:47]
	global_load_lds_dwordx4 v168, s[46:47]
	s_add_u32 m0, m0, 0x400
	s_waitcnt lgkmcnt(0)
	v_mfma_f32_32x32x16_bf16 v[16:31], v[112:115], v[124:127], v[16:31]
	v_mfma_f32_32x32x16_bf16 v[0:15], v[120:123], v[124:127], v[0:15]
	global_load_lds_dwordx4 v169, s[46:47]
	v_xor_b32_e32 v170, 0x8000, v170
	v_xor_b32_e32 v171, 0x8000, v171
	v_xor_b32_e32 v172, 0x8000, v172
	v_xor_b32_e32 v173, 0x8000, v173
	v_xor_b32_e32 v174, 0x8000, v174
	v_xor_b32_e32 v175, 0x8000, v175
	v_xor_b32_e32 v176, 0x8000, v176
	v_xor_b32_e32 v177, 0x8000, v177
	s_xor_b32 s14, s14, 0x8000
	s_add_u32 s10, s10, 128
	s_addc_u32 s11, s11, 0
	s_add_u32 s46, s46, 128
	s_addc_u32 s47, s47, 0
	s_add_u32 s13, s13, 1
	s_waitcnt vmcnt(0)
	s_cmp_lt_u32 s13, 15
	s_barrier
	s_cbranch_scc1 .LBB0_450
.Lp1k_tail:
	ds_read_b128 v[64:67], v174
	ds_read_b128 v[68:71], v170
	ds_read_b128 v[72:75], v174 offset:4096
	ds_read_b128 v[76:79], v170 offset:4096
	ds_read_b128 v[80:83], v175
	ds_read_b128 v[84:87], v171
	ds_read_b128 v[88:91], v175 offset:4096
	ds_read_b128 v[92:95], v171 offset:4096
	ds_read_b128 v[96:99], v176
	ds_read_b128 v[100:103], v172
	ds_read_b128 v[104:107], v176 offset:4096
	ds_read_b128 v[108:111], v172 offset:4096
	ds_read_b128 v[112:115], v177
	ds_read_b128 v[116:119], v173
	ds_read_b128 v[120:123], v177 offset:4096
	ds_read_b128 v[124:127], v173 offset:4096
	s_waitcnt lgkmcnt(14)
	v_mfma_f32_32x32x16_bf16 v[48:63], v[64:67], v[68:71], v[48:63]
	s_waitcnt lgkmcnt(13)
	v_mfma_f32_32x32x16_bf16 v[32:47], v[72:75], v[68:71], v[32:47]
	s_waitcnt lgkmcnt(12)
	v_mfma_f32_32x32x16_bf16 v[16:31], v[64:67], v[76:79], v[16:31]
	v_mfma_f32_32x32x16_bf16 v[0:15], v[72:75], v[76:79], v[0:15]
	s_waitcnt lgkmcnt(10)
	v_mfma_f32_32x32x16_bf16 v[48:63], v[80:83], v[84:87], v[48:63]
	s_waitcnt lgkmcnt(9)
	v_mfma_f32_32x32x16_bf16 v[32:47], v[88:91], v[84:87], v[32:47]
	s_waitcnt lgkmcnt(8)
	v_mfma_f32_32x32x16_bf16 v[16:31], v[80:83], v[92:95], v[16:31]
	v_mfma_f32_32x32x16_bf16 v[0:15], v[88:91], v[92:95], v[0:15]
	s_waitcnt lgkmcnt(6)
	v_mfma_f32_32x32x16_bf16 v[48:63], v[96:99], v[100:103], v[48:63]
	s_waitcnt lgkmcnt(5)
	v_mfma_f32_32x32x16_bf16 v[32:47], v[104:107], v[100:103], v[32:47]
	s_waitcnt lgkmcnt(4)
	v_mfma_f32_32x32x16_bf16 v[16:31], v[96:99], v[108:111], v[16:31]
	v_mfma_f32_32x32x16_bf16 v[0:15], v[104:107], v[108:111], v[0:15]
	s_waitcnt lgkmcnt(2)
	v_mfma_f32_32x32x16_bf16 v[48:63], v[112:115], v[116:119], v[48:63]
	s_waitcnt lgkmcnt(1)
	v_mfma_f32_32x32x16_bf16 v[32:47], v[120:123], v[116:119], v[32:47]
	s_waitcnt lgkmcnt(0)
	v_mfma_f32_32x32x16_bf16 v[16:31], v[112:115], v[124:127], v[16:31]
	v_mfma_f32_32x32x16_bf16 v[0:15], v[120:123], v[124:127], v[0:15]
	v_xor_b32_e32 v170, 0x8000, v170
	v_xor_b32_e32 v171, 0x8000, v171
	v_xor_b32_e32 v172, 0x8000, v172
	v_xor_b32_e32 v173, 0x8000, v173
	v_xor_b32_e32 v174, 0x8000, v174
	v_xor_b32_e32 v175, 0x8000, v175
	v_xor_b32_e32 v176, 0x8000, v176
	v_xor_b32_e32 v177, 0x8000, v177
	s_add_u32 s13, s13, 1
	s_waitcnt vmcnt(0)
	s_cmp_lt_u32 s13, 16
	s_barrier
	s_branch .LBB0_447
